# v40 + SwiGLU epilogue of both F1 sites with packed f32 mul/add on register pairs (same f32 arithmetic), 8 chains interleaved
# baseline (speedup 1.0000x reference)
.LBB0_840:
	v_lshl_or_b32 v148, s36, 7, v144
	v_lshl_add_u32 v146, s37, 8, v142
	v_ashrrev_i32_e32 v149, 31, v148
	v_mov_b64_e32 v[140:141], s[78:79]
	v_mad_i64_i32 v[150:151], s[0:1], v146, s13, v[140:141]
	s_mov_b64 s[18:19], -1
	s_andn2_b64 vcc, exec, s[2:3]
	s_mov_b32 s100, 0xbfb8aa3b
	v_lshlrev_b64 v[184:185], 1, v[148:149]
	v_pk_mul_f32 v[152:153], v[126:127], s[100:101] op_sel_hi:[1,0]
	v_pk_mul_f32 v[154:155], v[128:129], s[100:101] op_sel_hi:[1,0]
	v_pk_mul_f32 v[156:157], v[118:119], s[100:101] op_sel_hi:[1,0]
	v_pk_mul_f32 v[158:159], v[120:121], s[100:101] op_sel_hi:[1,0]
	v_exp_f32_e32 v152, v152
	v_exp_f32_e32 v153, v153
	v_exp_f32_e32 v154, v154
	v_exp_f32_e32 v155, v155
	v_exp_f32_e32 v156, v156
	v_exp_f32_e32 v157, v157
	v_exp_f32_e32 v158, v158
	v_exp_f32_e32 v159, v159
	v_pk_add_f32 v[152:153], v[152:153], 1.0 op_sel_hi:[1,0]
	v_pk_add_f32 v[154:155], v[154:155], 1.0 op_sel_hi:[1,0]
	v_pk_add_f32 v[156:157], v[156:157], 1.0 op_sel_hi:[1,0]
	v_pk_add_f32 v[158:159], v[158:159], 1.0 op_sel_hi:[1,0]
	v_rcp_f32_e32 v152, v152
	v_rcp_f32_e32 v153, v153
	v_rcp_f32_e32 v154, v154
	v_rcp_f32_e32 v155, v155
	v_rcp_f32_e32 v156, v156
	v_rcp_f32_e32 v157, v157
	v_rcp_f32_e32 v158, v158
	v_rcp_f32_e32 v159, v159
	v_pk_mul_f32 v[126:127], v[126:127], v[152:153]
	v_pk_mul_f32 v[128:129], v[128:129], v[154:155]
	v_pk_mul_f32 v[118:119], v[118:119], v[156:157]
	v_pk_mul_f32 v[120:121], v[120:121], v[158:159]
	v_lshl_add_u64 v[164:165], v[150:151], 0, v[184:185]
	v_pk_mul_f32 v[122:123], v[126:127], v[122:123]
	v_pk_mul_f32 v[124:125], v[128:129], v[124:125]
	v_pk_mul_f32 v[114:115], v[118:119], v[114:115]
	v_pk_mul_f32 v[116:117], v[120:121], v[116:117]
	v_cvt_pk_bf16_f32 v160, v122, v123
	v_cvt_pk_bf16_f32 v161, v124, v125
	v_cvt_pk_bf16_f32 v162, v114, v115
	v_cvt_pk_bf16_f32 v163, v116, v117
	s_nop 0
	global_store_dwordx4 v[164:165], v[160:163], off
	v_pk_mul_f32 v[168:169], v[110:111], s[100:101] op_sel_hi:[1,0]
	v_pk_mul_f32 v[170:171], v[112:113], s[100:101] op_sel_hi:[1,0]
	v_pk_mul_f32 v[172:173], v[102:103], s[100:101] op_sel_hi:[1,0]
	v_pk_mul_f32 v[174:175], v[104:105], s[100:101] op_sel_hi:[1,0]
	v_exp_f32_e32 v168, v168
	v_exp_f32_e32 v169, v169
	v_exp_f32_e32 v170, v170
	v_exp_f32_e32 v171, v171
	v_exp_f32_e32 v172, v172
	v_exp_f32_e32 v173, v173
	v_exp_f32_e32 v174, v174
	v_exp_f32_e32 v175, v175
	v_pk_add_f32 v[168:169], v[168:169], 1.0 op_sel_hi:[1,0]
	v_pk_add_f32 v[170:171], v[170:171], 1.0 op_sel_hi:[1,0]
	v_pk_add_f32 v[172:173], v[172:173], 1.0 op_sel_hi:[1,0]
	v_pk_add_f32 v[174:175], v[174:175], 1.0 op_sel_hi:[1,0]
	v_rcp_f32_e32 v168, v168
	v_rcp_f32_e32 v169, v169
	v_rcp_f32_e32 v170, v170
	v_rcp_f32_e32 v171, v171
	v_rcp_f32_e32 v172, v172
	v_rcp_f32_e32 v173, v173
	v_rcp_f32_e32 v174, v174
	v_rcp_f32_e32 v175, v175
	v_pk_mul_f32 v[110:111], v[110:111], v[168:169]
	v_pk_mul_f32 v[112:113], v[112:113], v[170:171]
	v_pk_mul_f32 v[102:103], v[102:103], v[172:173]
	v_pk_mul_f32 v[104:105], v[104:105], v[174:175]
	v_or_b32_e32 v182, 16, v146
	v_pk_mul_f32 v[106:107], v[110:111], v[106:107]
	v_pk_mul_f32 v[108:109], v[112:113], v[108:109]
	v_pk_mul_f32 v[98:99], v[102:103], v[98:99]
	v_pk_mul_f32 v[100:101], v[104:105], v[100:101]
	v_mad_i64_i32 v[180:181], s[0:1], v182, s13, v[140:141]
	v_cvt_pk_bf16_f32 v176, v106, v107
	v_cvt_pk_bf16_f32 v177, v108, v109
	v_cvt_pk_bf16_f32 v178, v98, v99
	v_cvt_pk_bf16_f32 v179, v100, v101
	v_lshl_add_u64 v[180:181], v[180:181], 0, v[184:185]
	global_store_dwordx4 v[180:181], v[176:179], off
	v_pk_mul_f32 v[152:153], v[94:95], s[100:101] op_sel_hi:[1,0]
	v_pk_mul_f32 v[154:155], v[96:97], s[100:101] op_sel_hi:[1,0]
	v_pk_mul_f32 v[156:157], v[86:87], s[100:101] op_sel_hi:[1,0]
	v_pk_mul_f32 v[158:159], v[88:89], s[100:101] op_sel_hi:[1,0]
	v_exp_f32_e32 v152, v152
	v_exp_f32_e32 v153, v153
	v_exp_f32_e32 v154, v154
	v_exp_f32_e32 v155, v155
	v_exp_f32_e32 v156, v156
	v_exp_f32_e32 v157, v157
	v_exp_f32_e32 v158, v158
	v_exp_f32_e32 v159, v159
	v_pk_add_f32 v[152:153], v[152:153], 1.0 op_sel_hi:[1,0]
	v_pk_add_f32 v[154:155], v[154:155], 1.0 op_sel_hi:[1,0]
	v_pk_add_f32 v[156:157], v[156:157], 1.0 op_sel_hi:[1,0]
	v_pk_add_f32 v[158:159], v[158:159], 1.0 op_sel_hi:[1,0]
	v_rcp_f32_e32 v152, v152
	v_rcp_f32_e32 v153, v153
	v_rcp_f32_e32 v154, v154
	v_rcp_f32_e32 v155, v155
	v_rcp_f32_e32 v156, v156
	v_rcp_f32_e32 v157, v157
	v_rcp_f32_e32 v158, v158
	v_rcp_f32_e32 v159, v159
	v_pk_mul_f32 v[94:95], v[94:95], v[152:153]
	v_pk_mul_f32 v[96:97], v[96:97], v[154:155]
	v_pk_mul_f32 v[86:87], v[86:87], v[156:157]
	v_pk_mul_f32 v[88:89], v[88:89], v[158:159]
	v_or_b32_e32 v166, 32, v146
	v_pk_mul_f32 v[90:91], v[94:95], v[90:91]
	v_pk_mul_f32 v[92:93], v[96:97], v[92:93]
	v_pk_mul_f32 v[82:83], v[86:87], v[82:83]
	v_pk_mul_f32 v[84:85], v[88:89], v[84:85]
	v_mad_i64_i32 v[164:165], s[0:1], v166, s13, v[140:141]
	v_cvt_pk_bf16_f32 v160, v90, v91
	v_cvt_pk_bf16_f32 v161, v92, v93
	v_cvt_pk_bf16_f32 v162, v82, v83
	v_cvt_pk_bf16_f32 v163, v84, v85
	v_lshl_add_u64 v[164:165], v[164:165], 0, v[184:185]
	global_store_dwordx4 v[164:165], v[160:163], off
	v_pk_mul_f32 v[168:169], v[78:79], s[100:101] op_sel_hi:[1,0]
	v_pk_mul_f32 v[170:171], v[80:81], s[100:101] op_sel_hi:[1,0]
	v_pk_mul_f32 v[172:173], v[70:71], s[100:101] op_sel_hi:[1,0]
	v_pk_mul_f32 v[174:175], v[72:73], s[100:101] op_sel_hi:[1,0]
	v_exp_f32_e32 v168, v168
	v_exp_f32_e32 v169, v169
	v_exp_f32_e32 v170, v170
	v_exp_f32_e32 v171, v171
	v_exp_f32_e32 v172, v172
	v_exp_f32_e32 v173, v173
	v_exp_f32_e32 v174, v174
	v_exp_f32_e32 v175, v175
	v_pk_add_f32 v[168:169], v[168:169], 1.0 op_sel_hi:[1,0]
	v_pk_add_f32 v[170:171], v[170:171], 1.0 op_sel_hi:[1,0]
	v_pk_add_f32 v[172:173], v[172:173], 1.0 op_sel_hi:[1,0]
	v_pk_add_f32 v[174:175], v[174:175], 1.0 op_sel_hi:[1,0]
	v_rcp_f32_e32 v168, v168
	v_rcp_f32_e32 v169, v169
	v_rcp_f32_e32 v170, v170
	v_rcp_f32_e32 v171, v171
	v_rcp_f32_e32 v172, v172
	v_rcp_f32_e32 v173, v173
	v_rcp_f32_e32 v174, v174
	v_rcp_f32_e32 v175, v175
	v_pk_mul_f32 v[78:79], v[78:79], v[168:169]
	v_pk_mul_f32 v[80:81], v[80:81], v[170:171]
	v_pk_mul_f32 v[70:71], v[70:71], v[172:173]
	v_pk_mul_f32 v[72:73], v[72:73], v[174:175]
	v_or_b32_e32 v182, 48, v146
	v_pk_mul_f32 v[74:75], v[78:79], v[74:75]
	v_pk_mul_f32 v[76:77], v[80:81], v[76:77]
	v_pk_mul_f32 v[66:67], v[70:71], v[66:67]
	v_pk_mul_f32 v[68:69], v[72:73], v[68:69]
	v_mad_i64_i32 v[180:181], s[0:1], v182, s13, v[140:141]
	v_cvt_pk_bf16_f32 v176, v74, v75
	v_cvt_pk_bf16_f32 v177, v76, v77
	v_cvt_pk_bf16_f32 v178, v66, v67
	v_cvt_pk_bf16_f32 v179, v68, v69
	v_lshl_add_u64 v[180:181], v[180:181], 0, v[184:185]
	global_store_dwordx4 v[180:181], v[176:179], off
	v_pk_mul_f32 v[152:153], v[62:63], s[100:101] op_sel_hi:[1,0]
	v_pk_mul_f32 v[154:155], v[64:65], s[100:101] op_sel_hi:[1,0]
	v_pk_mul_f32 v[156:157], v[54:55], s[100:101] op_sel_hi:[1,0]
	v_pk_mul_f32 v[158:159], v[56:57], s[100:101] op_sel_hi:[1,0]
	v_exp_f32_e32 v152, v152
	v_exp_f32_e32 v153, v153
	v_exp_f32_e32 v154, v154
	v_exp_f32_e32 v155, v155
	v_exp_f32_e32 v156, v156
	v_exp_f32_e32 v157, v157
	v_exp_f32_e32 v158, v158
	v_exp_f32_e32 v159, v159
	v_pk_add_f32 v[152:153], v[152:153], 1.0 op_sel_hi:[1,0]
	v_pk_add_f32 v[154:155], v[154:155], 1.0 op_sel_hi:[1,0]
	v_pk_add_f32 v[156:157], v[156:157], 1.0 op_sel_hi:[1,0]
	v_pk_add_f32 v[158:159], v[158:159], 1.0 op_sel_hi:[1,0]
	v_rcp_f32_e32 v152, v152
	v_rcp_f32_e32 v153, v153
	v_rcp_f32_e32 v154, v154
	v_rcp_f32_e32 v155, v155
	v_rcp_f32_e32 v156, v156
	v_rcp_f32_e32 v157, v157
	v_rcp_f32_e32 v158, v158
	v_rcp_f32_e32 v159, v159
	v_pk_mul_f32 v[62:63], v[62:63], v[152:153]
	v_pk_mul_f32 v[64:65], v[64:65], v[154:155]
	v_pk_mul_f32 v[54:55], v[54:55], v[156:157]
	v_pk_mul_f32 v[56:57], v[56:57], v[158:159]
	v_add_u32_e32 v166, 0x80, v146
	v_pk_mul_f32 v[58:59], v[62:63], v[58:59]
	v_pk_mul_f32 v[60:61], v[64:65], v[60:61]
	v_pk_mul_f32 v[50:51], v[54:55], v[50:51]
	v_pk_mul_f32 v[52:53], v[56:57], v[52:53]
	v_mad_i64_i32 v[164:165], s[0:1], v166, s13, v[140:141]
	v_cvt_pk_bf16_f32 v160, v58, v59
	v_cvt_pk_bf16_f32 v161, v60, v61
	v_cvt_pk_bf16_f32 v162, v50, v51
	v_cvt_pk_bf16_f32 v163, v52, v53
	v_lshl_add_u64 v[164:165], v[164:165], 0, v[184:185]
	global_store_dwordx4 v[164:165], v[160:163], off
	v_pk_mul_f32 v[168:169], v[46:47], s[100:101] op_sel_hi:[1,0]
	v_pk_mul_f32 v[170:171], v[48:49], s[100:101] op_sel_hi:[1,0]
	v_pk_mul_f32 v[172:173], v[38:39], s[100:101] op_sel_hi:[1,0]
	v_pk_mul_f32 v[174:175], v[40:41], s[100:101] op_sel_hi:[1,0]
	v_exp_f32_e32 v168, v168
	v_exp_f32_e32 v169, v169
	v_exp_f32_e32 v170, v170
	v_exp_f32_e32 v171, v171
	v_exp_f32_e32 v172, v172
	v_exp_f32_e32 v173, v173
	v_exp_f32_e32 v174, v174
	v_exp_f32_e32 v175, v175
	v_pk_add_f32 v[168:169], v[168:169], 1.0 op_sel_hi:[1,0]
	v_pk_add_f32 v[170:171], v[170:171], 1.0 op_sel_hi:[1,0]
	v_pk_add_f32 v[172:173], v[172:173], 1.0 op_sel_hi:[1,0]
	v_pk_add_f32 v[174:175], v[174:175], 1.0 op_sel_hi:[1,0]
	v_rcp_f32_e32 v168, v168
	v_rcp_f32_e32 v169, v169
	v_rcp_f32_e32 v170, v170
	v_rcp_f32_e32 v171, v171
	v_rcp_f32_e32 v172, v172
	v_rcp_f32_e32 v173, v173
	v_rcp_f32_e32 v174, v174
	v_rcp_f32_e32 v175, v175
	v_pk_mul_f32 v[46:47], v[46:47], v[168:169]
	v_pk_mul_f32 v[48:49], v[48:49], v[170:171]
	v_pk_mul_f32 v[38:39], v[38:39], v[172:173]
	v_pk_mul_f32 v[40:41], v[40:41], v[174:175]
	v_add_u32_e32 v182, 0x90, v146
	v_pk_mul_f32 v[42:43], v[46:47], v[42:43]
	v_pk_mul_f32 v[44:45], v[48:49], v[44:45]
	v_pk_mul_f32 v[34:35], v[38:39], v[34:35]
	v_pk_mul_f32 v[36:37], v[40:41], v[36:37]
	v_mad_i64_i32 v[180:181], s[0:1], v182, s13, v[140:141]
	v_cvt_pk_bf16_f32 v176, v42, v43
	v_cvt_pk_bf16_f32 v177, v44, v45
	v_cvt_pk_bf16_f32 v178, v34, v35
	v_cvt_pk_bf16_f32 v179, v36, v37
	v_lshl_add_u64 v[180:181], v[180:181], 0, v[184:185]
	global_store_dwordx4 v[180:181], v[176:179], off
	v_pk_mul_f32 v[152:153], v[30:31], s[100:101] op_sel_hi:[1,0]
	v_pk_mul_f32 v[154:155], v[32:33], s[100:101] op_sel_hi:[1,0]
	v_pk_mul_f32 v[156:157], v[22:23], s[100:101] op_sel_hi:[1,0]
	v_pk_mul_f32 v[158:159], v[24:25], s[100:101] op_sel_hi:[1,0]
	v_exp_f32_e32 v152, v152
	v_exp_f32_e32 v153, v153
	v_exp_f32_e32 v154, v154
	v_exp_f32_e32 v155, v155
	v_exp_f32_e32 v156, v156
	v_exp_f32_e32 v157, v157
	v_exp_f32_e32 v158, v158
	v_exp_f32_e32 v159, v159
	v_pk_add_f32 v[152:153], v[152:153], 1.0 op_sel_hi:[1,0]
	v_pk_add_f32 v[154:155], v[154:155], 1.0 op_sel_hi:[1,0]
	v_pk_add_f32 v[156:157], v[156:157], 1.0 op_sel_hi:[1,0]
	v_pk_add_f32 v[158:159], v[158:159], 1.0 op_sel_hi:[1,0]
	v_rcp_f32_e32 v152, v152
	v_rcp_f32_e32 v153, v153
	v_rcp_f32_e32 v154, v154
	v_rcp_f32_e32 v155, v155
	v_rcp_f32_e32 v156, v156
	v_rcp_f32_e32 v157, v157
	v_rcp_f32_e32 v158, v158
	v_rcp_f32_e32 v159, v159
	v_pk_mul_f32 v[30:31], v[30:31], v[152:153]
	v_pk_mul_f32 v[32:33], v[32:33], v[154:155]
	v_pk_mul_f32 v[22:23], v[22:23], v[156:157]
	v_pk_mul_f32 v[24:25], v[24:25], v[158:159]
	v_add_u32_e32 v166, 0xa0, v146
	v_pk_mul_f32 v[26:27], v[30:31], v[26:27]
	v_pk_mul_f32 v[28:29], v[32:33], v[28:29]
	v_pk_mul_f32 v[18:19], v[22:23], v[18:19]
	v_pk_mul_f32 v[20:21], v[24:25], v[20:21]
	v_mad_i64_i32 v[164:165], s[0:1], v166, s13, v[140:141]
	v_cvt_pk_bf16_f32 v160, v26, v27
	v_cvt_pk_bf16_f32 v161, v28, v29
	v_cvt_pk_bf16_f32 v162, v18, v19
	v_cvt_pk_bf16_f32 v163, v20, v21
	v_lshl_add_u64 v[164:165], v[164:165], 0, v[184:185]
	global_store_dwordx4 v[164:165], v[160:163], off
	v_pk_mul_f32 v[168:169], v[14:15], s[100:101] op_sel_hi:[1,0]
	v_pk_mul_f32 v[170:171], v[16:17], s[100:101] op_sel_hi:[1,0]
	v_pk_mul_f32 v[172:173], v[6:7], s[100:101] op_sel_hi:[1,0]
	v_pk_mul_f32 v[174:175], v[8:9], s[100:101] op_sel_hi:[1,0]
	v_exp_f32_e32 v168, v168
	v_exp_f32_e32 v169, v169
	v_exp_f32_e32 v170, v170
	v_exp_f32_e32 v171, v171
	v_exp_f32_e32 v172, v172
	v_exp_f32_e32 v173, v173
	v_exp_f32_e32 v174, v174
	v_exp_f32_e32 v175, v175
	v_pk_add_f32 v[168:169], v[168:169], 1.0 op_sel_hi:[1,0]
	v_pk_add_f32 v[170:171], v[170:171], 1.0 op_sel_hi:[1,0]
	v_pk_add_f32 v[172:173], v[172:173], 1.0 op_sel_hi:[1,0]
	v_pk_add_f32 v[174:175], v[174:175], 1.0 op_sel_hi:[1,0]
	v_rcp_f32_e32 v168, v168
	v_rcp_f32_e32 v169, v169
	v_rcp_f32_e32 v170, v170
	v_rcp_f32_e32 v171, v171
	v_rcp_f32_e32 v172, v172
	v_rcp_f32_e32 v173, v173
	v_rcp_f32_e32 v174, v174
	v_rcp_f32_e32 v175, v175
	v_pk_mul_f32 v[14:15], v[14:15], v[168:169]
	v_pk_mul_f32 v[16:17], v[16:17], v[170:171]
	v_pk_mul_f32 v[6:7], v[6:7], v[172:173]
	v_pk_mul_f32 v[8:9], v[8:9], v[174:175]
	v_add_u32_e32 v182, 0xb0, v146
	v_pk_mul_f32 v[10:11], v[14:15], v[10:11]
	v_pk_mul_f32 v[12:13], v[16:17], v[12:13]
	v_pk_mul_f32 v[2:3], v[6:7], v[2:3]
	v_pk_mul_f32 v[4:5], v[8:9], v[4:5]
	v_mad_i64_i32 v[180:181], s[0:1], v182, s13, v[140:141]
	v_cvt_pk_bf16_f32 v176, v10, v11
	v_cvt_pk_bf16_f32 v177, v12, v13
	v_cvt_pk_bf16_f32 v178, v2, v3
	v_cvt_pk_bf16_f32 v179, v4, v5
	v_lshl_add_u64 v[180:181], v[180:181], 0, v[184:185]
	global_store_dwordx4 v[180:181], v[176:179], off
	s_cbranch_vccnz .LBB0_833
	s_andn2_b64 vcc, exec, s[4:5]
	s_cbranch_vccnz .LBB0_832
	s_barrier
	s_branch .LBB0_832

.LBB0_1597:
	v_lshl_or_b32 v148, s24, 7, v144
	v_lshl_add_u32 v146, s26, 8, v142
	v_ashrrev_i32_e32 v149, 31, v148
	v_mov_b64_e32 v[140:141], s[78:79]
	v_mad_i64_i32 v[150:151], s[0:1], v146, s13, v[140:141]
	s_mov_b64 s[2:3], -1
	s_andn2_b64 vcc, exec, s[8:9]
	s_mov_b32 s100, 0xbfb8aa3b
	v_lshlrev_b64 v[184:185], 1, v[148:149]
	v_pk_mul_f32 v[152:153], v[126:127], s[100:101] op_sel_hi:[1,0]
	v_pk_mul_f32 v[154:155], v[128:129], s[100:101] op_sel_hi:[1,0]
	v_pk_mul_f32 v[156:157], v[118:119], s[100:101] op_sel_hi:[1,0]
	v_pk_mul_f32 v[158:159], v[120:121], s[100:101] op_sel_hi:[1,0]
	v_exp_f32_e32 v152, v152
	v_exp_f32_e32 v153, v153
	v_exp_f32_e32 v154, v154
	v_exp_f32_e32 v155, v155
	v_exp_f32_e32 v156, v156
	v_exp_f32_e32 v157, v157
	v_exp_f32_e32 v158, v158
	v_exp_f32_e32 v159, v159
	v_pk_add_f32 v[152:153], v[152:153], 1.0 op_sel_hi:[1,0]
	v_pk_add_f32 v[154:155], v[154:155], 1.0 op_sel_hi:[1,0]
	v_pk_add_f32 v[156:157], v[156:157], 1.0 op_sel_hi:[1,0]
	v_pk_add_f32 v[158:159], v[158:159], 1.0 op_sel_hi:[1,0]
	v_rcp_f32_e32 v152, v152
	v_rcp_f32_e32 v153, v153
	v_rcp_f32_e32 v154, v154
	v_rcp_f32_e32 v155, v155
	v_rcp_f32_e32 v156, v156
	v_rcp_f32_e32 v157, v157
	v_rcp_f32_e32 v158, v158
	v_rcp_f32_e32 v159, v159
	v_pk_mul_f32 v[126:127], v[126:127], v[152:153]
	v_pk_mul_f32 v[128:129], v[128:129], v[154:155]
	v_pk_mul_f32 v[118:119], v[118:119], v[156:157]
	v_pk_mul_f32 v[120:121], v[120:121], v[158:159]
	v_lshl_add_u64 v[164:165], v[150:151], 0, v[184:185]
	v_pk_mul_f32 v[122:123], v[126:127], v[122:123]
	v_pk_mul_f32 v[124:125], v[128:129], v[124:125]
	v_pk_mul_f32 v[114:115], v[118:119], v[114:115]
	v_pk_mul_f32 v[116:117], v[120:121], v[116:117]
	v_cvt_pk_bf16_f32 v160, v122, v123
	v_cvt_pk_bf16_f32 v161, v124, v125
	v_cvt_pk_bf16_f32 v162, v114, v115
	v_cvt_pk_bf16_f32 v163, v116, v117
	s_nop 0
	global_store_dwordx4 v[164:165], v[160:163], off
	v_pk_mul_f32 v[168:169], v[110:111], s[100:101] op_sel_hi:[1,0]
	v_pk_mul_f32 v[170:171], v[112:113], s[100:101] op_sel_hi:[1,0]
	v_pk_mul_f32 v[172:173], v[102:103], s[100:101] op_sel_hi:[1,0]
	v_pk_mul_f32 v[174:175], v[104:105], s[100:101] op_sel_hi:[1,0]
	v_exp_f32_e32 v168, v168
	v_exp_f32_e32 v169, v169
	v_exp_f32_e32 v170, v170
	v_exp_f32_e32 v171, v171
	v_exp_f32_e32 v172, v172
	v_exp_f32_e32 v173, v173
	v_exp_f32_e32 v174, v174
	v_exp_f32_e32 v175, v175
	v_pk_add_f32 v[168:169], v[168:169], 1.0 op_sel_hi:[1,0]
	v_pk_add_f32 v[170:171], v[170:171], 1.0 op_sel_hi:[1,0]
	v_pk_add_f32 v[172:173], v[172:173], 1.0 op_sel_hi:[1,0]
	v_pk_add_f32 v[174:175], v[174:175], 1.0 op_sel_hi:[1,0]
	v_rcp_f32_e32 v168, v168
	v_rcp_f32_e32 v169, v169
	v_rcp_f32_e32 v170, v170
	v_rcp_f32_e32 v171, v171
	v_rcp_f32_e32 v172, v172
	v_rcp_f32_e32 v173, v173
	v_rcp_f32_e32 v174, v174
	v_rcp_f32_e32 v175, v175
	v_pk_mul_f32 v[110:111], v[110:111], v[168:169]
	v_pk_mul_f32 v[112:113], v[112:113], v[170:171]
	v_pk_mul_f32 v[102:103], v[102:103], v[172:173]
	v_pk_mul_f32 v[104:105], v[104:105], v[174:175]
	v_or_b32_e32 v182, 16, v146
	v_pk_mul_f32 v[106:107], v[110:111], v[106:107]
	v_pk_mul_f32 v[108:109], v[112:113], v[108:109]
	v_pk_mul_f32 v[98:99], v[102:103], v[98:99]
	v_pk_mul_f32 v[100:101], v[104:105], v[100:101]
	v_mad_i64_i32 v[180:181], s[0:1], v182, s13, v[140:141]
	v_cvt_pk_bf16_f32 v176, v106, v107
	v_cvt_pk_bf16_f32 v177, v108, v109
	v_cvt_pk_bf16_f32 v178, v98, v99
	v_cvt_pk_bf16_f32 v179, v100, v101
	v_lshl_add_u64 v[180:181], v[180:181], 0, v[184:185]
	global_store_dwordx4 v[180:181], v[176:179], off
	v_pk_mul_f32 v[152:153], v[94:95], s[100:101] op_sel_hi:[1,0]
	v_pk_mul_f32 v[154:155], v[96:97], s[100:101] op_sel_hi:[1,0]
	v_pk_mul_f32 v[156:157], v[86:87], s[100:101] op_sel_hi:[1,0]
	v_pk_mul_f32 v[158:159], v[88:89], s[100:101] op_sel_hi:[1,0]
	v_exp_f32_e32 v152, v152
	v_exp_f32_e32 v153, v153
	v_exp_f32_e32 v154, v154
	v_exp_f32_e32 v155, v155
	v_exp_f32_e32 v156, v156
	v_exp_f32_e32 v157, v157
	v_exp_f32_e32 v158, v158
	v_exp_f32_e32 v159, v159
	v_pk_add_f32 v[152:153], v[152:153], 1.0 op_sel_hi:[1,0]
	v_pk_add_f32 v[154:155], v[154:155], 1.0 op_sel_hi:[1,0]
	v_pk_add_f32 v[156:157], v[156:157], 1.0 op_sel_hi:[1,0]
	v_pk_add_f32 v[158:159], v[158:159], 1.0 op_sel_hi:[1,0]
	v_rcp_f32_e32 v152, v152
	v_rcp_f32_e32 v153, v153
	v_rcp_f32_e32 v154, v154
	v_rcp_f32_e32 v155, v155
	v_rcp_f32_e32 v156, v156
	v_rcp_f32_e32 v157, v157
	v_rcp_f32_e32 v158, v158
	v_rcp_f32_e32 v159, v159
	v_pk_mul_f32 v[94:95], v[94:95], v[152:153]
	v_pk_mul_f32 v[96:97], v[96:97], v[154:155]
	v_pk_mul_f32 v[86:87], v[86:87], v[156:157]
	v_pk_mul_f32 v[88:89], v[88:89], v[158:159]
	v_or_b32_e32 v166, 32, v146
	v_pk_mul_f32 v[90:91], v[94:95], v[90:91]
	v_pk_mul_f32 v[92:93], v[96:97], v[92:93]
	v_pk_mul_f32 v[82:83], v[86:87], v[82:83]
	v_pk_mul_f32 v[84:85], v[88:89], v[84:85]
	v_mad_i64_i32 v[164:165], s[0:1], v166, s13, v[140:141]
	v_cvt_pk_bf16_f32 v160, v90, v91
	v_cvt_pk_bf16_f32 v161, v92, v93
	v_cvt_pk_bf16_f32 v162, v82, v83
	v_cvt_pk_bf16_f32 v163, v84, v85
	v_lshl_add_u64 v[164:165], v[164:165], 0, v[184:185]
	global_store_dwordx4 v[164:165], v[160:163], off
	v_pk_mul_f32 v[168:169], v[78:79], s[100:101] op_sel_hi:[1,0]
	v_pk_mul_f32 v[170:171], v[80:81], s[100:101] op_sel_hi:[1,0]
	v_pk_mul_f32 v[172:173], v[70:71], s[100:101] op_sel_hi:[1,0]
	v_pk_mul_f32 v[174:175], v[72:73], s[100:101] op_sel_hi:[1,0]
	v_exp_f32_e32 v168, v168
	v_exp_f32_e32 v169, v169
	v_exp_f32_e32 v170, v170
	v_exp_f32_e32 v171, v171
	v_exp_f32_e32 v172, v172
	v_exp_f32_e32 v173, v173
	v_exp_f32_e32 v174, v174
	v_exp_f32_e32 v175, v175
	v_pk_add_f32 v[168:169], v[168:169], 1.0 op_sel_hi:[1,0]
	v_pk_add_f32 v[170:171], v[170:171], 1.0 op_sel_hi:[1,0]
	v_pk_add_f32 v[172:173], v[172:173], 1.0 op_sel_hi:[1,0]
	v_pk_add_f32 v[174:175], v[174:175], 1.0 op_sel_hi:[1,0]
	v_rcp_f32_e32 v168, v168
	v_rcp_f32_e32 v169, v169
	v_rcp_f32_e32 v170, v170
	v_rcp_f32_e32 v171, v171
	v_rcp_f32_e32 v172, v172
	v_rcp_f32_e32 v173, v173
	v_rcp_f32_e32 v174, v174
	v_rcp_f32_e32 v175, v175
	v_pk_mul_f32 v[78:79], v[78:79], v[168:169]
	v_pk_mul_f32 v[80:81], v[80:81], v[170:171]
	v_pk_mul_f32 v[70:71], v[70:71], v[172:173]
	v_pk_mul_f32 v[72:73], v[72:73], v[174:175]
	v_or_b32_e32 v182, 48, v146
	v_pk_mul_f32 v[74:75], v[78:79], v[74:75]
	v_pk_mul_f32 v[76:77], v[80:81], v[76:77]
	v_pk_mul_f32 v[66:67], v[70:71], v[66:67]
	v_pk_mul_f32 v[68:69], v[72:73], v[68:69]
	v_mad_i64_i32 v[180:181], s[0:1], v182, s13, v[140:141]
	v_cvt_pk_bf16_f32 v176, v74, v75
	v_cvt_pk_bf16_f32 v177, v76, v77
	v_cvt_pk_bf16_f32 v178, v66, v67
	v_cvt_pk_bf16_f32 v179, v68, v69
	v_lshl_add_u64 v[180:181], v[180:181], 0, v[184:185]
	global_store_dwordx4 v[180:181], v[176:179], off
	v_pk_mul_f32 v[152:153], v[62:63], s[100:101] op_sel_hi:[1,0]
	v_pk_mul_f32 v[154:155], v[64:65], s[100:101] op_sel_hi:[1,0]
	v_pk_mul_f32 v[156:157], v[54:55], s[100:101] op_sel_hi:[1,0]
	v_pk_mul_f32 v[158:159], v[56:57], s[100:101] op_sel_hi:[1,0]
	v_exp_f32_e32 v152, v152
	v_exp_f32_e32 v153, v153
	v_exp_f32_e32 v154, v154
	v_exp_f32_e32 v155, v155
	v_exp_f32_e32 v156, v156
	v_exp_f32_e32 v157, v157
	v_exp_f32_e32 v158, v158
	v_exp_f32_e32 v159, v159
	v_pk_add_f32 v[152:153], v[152:153], 1.0 op_sel_hi:[1,0]
	v_pk_add_f32 v[154:155], v[154:155], 1.0 op_sel_hi:[1,0]
	v_pk_add_f32 v[156:157], v[156:157], 1.0 op_sel_hi:[1,0]
	v_pk_add_f32 v[158:159], v[158:159], 1.0 op_sel_hi:[1,0]
	v_rcp_f32_e32 v152, v152
	v_rcp_f32_e32 v153, v153
	v_rcp_f32_e32 v154, v154
	v_rcp_f32_e32 v155, v155
	v_rcp_f32_e32 v156, v156
	v_rcp_f32_e32 v157, v157
	v_rcp_f32_e32 v158, v158
	v_rcp_f32_e32 v159, v159
	v_pk_mul_f32 v[62:63], v[62:63], v[152:153]
	v_pk_mul_f32 v[64:65], v[64:65], v[154:155]
	v_pk_mul_f32 v[54:55], v[54:55], v[156:157]
	v_pk_mul_f32 v[56:57], v[56:57], v[158:159]
	v_add_u32_e32 v166, 0x80, v146
	v_pk_mul_f32 v[58:59], v[62:63], v[58:59]
	v_pk_mul_f32 v[60:61], v[64:65], v[60:61]
	v_pk_mul_f32 v[50:51], v[54:55], v[50:51]
	v_pk_mul_f32 v[52:53], v[56:57], v[52:53]
	v_mad_i64_i32 v[164:165], s[0:1], v166, s13, v[140:141]
	v_cvt_pk_bf16_f32 v160, v58, v59
	v_cvt_pk_bf16_f32 v161, v60, v61
	v_cvt_pk_bf16_f32 v162, v50, v51
	v_cvt_pk_bf16_f32 v163, v52, v53
	v_lshl_add_u64 v[164:165], v[164:165], 0, v[184:185]
	global_store_dwordx4 v[164:165], v[160:163], off
	v_pk_mul_f32 v[168:169], v[46:47], s[100:101] op_sel_hi:[1,0]
	v_pk_mul_f32 v[170:171], v[48:49], s[100:101] op_sel_hi:[1,0]
	v_pk_mul_f32 v[172:173], v[38:39], s[100:101] op_sel_hi:[1,0]
	v_pk_mul_f32 v[174:175], v[40:41], s[100:101] op_sel_hi:[1,0]
	v_exp_f32_e32 v168, v168
	v_exp_f32_e32 v169, v169
	v_exp_f32_e32 v170, v170
	v_exp_f32_e32 v171, v171
	v_exp_f32_e32 v172, v172
	v_exp_f32_e32 v173, v173
	v_exp_f32_e32 v174, v174
	v_exp_f32_e32 v175, v175
	v_pk_add_f32 v[168:169], v[168:169], 1.0 op_sel_hi:[1,0]
	v_pk_add_f32 v[170:171], v[170:171], 1.0 op_sel_hi:[1,0]
	v_pk_add_f32 v[172:173], v[172:173], 1.0 op_sel_hi:[1,0]
	v_pk_add_f32 v[174:175], v[174:175], 1.0 op_sel_hi:[1,0]
	v_rcp_f32_e32 v168, v168
	v_rcp_f32_e32 v169, v169
	v_rcp_f32_e32 v170, v170
	v_rcp_f32_e32 v171, v171
	v_rcp_f32_e32 v172, v172
	v_rcp_f32_e32 v173, v173
	v_rcp_f32_e32 v174, v174
	v_rcp_f32_e32 v175, v175
	v_pk_mul_f32 v[46:47], v[46:47], v[168:169]
	v_pk_mul_f32 v[48:49], v[48:49], v[170:171]
	v_pk_mul_f32 v[38:39], v[38:39], v[172:173]
	v_pk_mul_f32 v[40:41], v[40:41], v[174:175]
	v_add_u32_e32 v182, 0x90, v146
	v_pk_mul_f32 v[42:43], v[46:47], v[42:43]
	v_pk_mul_f32 v[44:45], v[48:49], v[44:45]
	v_pk_mul_f32 v[34:35], v[38:39], v[34:35]
	v_pk_mul_f32 v[36:37], v[40:41], v[36:37]
	v_mad_i64_i32 v[180:181], s[0:1], v182, s13, v[140:141]
	v_cvt_pk_bf16_f32 v176, v42, v43
	v_cvt_pk_bf16_f32 v177, v44, v45
	v_cvt_pk_bf16_f32 v178, v34, v35
	v_cvt_pk_bf16_f32 v179, v36, v37
	v_lshl_add_u64 v[180:181], v[180:181], 0, v[184:185]
	global_store_dwordx4 v[180:181], v[176:179], off
	v_pk_mul_f32 v[152:153], v[30:31], s[100:101] op_sel_hi:[1,0]
	v_pk_mul_f32 v[154:155], v[32:33], s[100:101] op_sel_hi:[1,0]
	v_pk_mul_f32 v[156:157], v[22:23], s[100:101] op_sel_hi:[1,0]
	v_pk_mul_f32 v[158:159], v[24:25], s[100:101] op_sel_hi:[1,0]
	v_exp_f32_e32 v152, v152
	v_exp_f32_e32 v153, v153
	v_exp_f32_e32 v154, v154
	v_exp_f32_e32 v155, v155
	v_exp_f32_e32 v156, v156
	v_exp_f32_e32 v157, v157
	v_exp_f32_e32 v158, v158
	v_exp_f32_e32 v159, v159
	v_pk_add_f32 v[152:153], v[152:153], 1.0 op_sel_hi:[1,0]
	v_pk_add_f32 v[154:155], v[154:155], 1.0 op_sel_hi:[1,0]
	v_pk_add_f32 v[156:157], v[156:157], 1.0 op_sel_hi:[1,0]
	v_pk_add_f32 v[158:159], v[158:159], 1.0 op_sel_hi:[1,0]
	v_rcp_f32_e32 v152, v152
	v_rcp_f32_e32 v153, v153
	v_rcp_f32_e32 v154, v154
	v_rcp_f32_e32 v155, v155
	v_rcp_f32_e32 v156, v156
	v_rcp_f32_e32 v157, v157
	v_rcp_f32_e32 v158, v158
	v_rcp_f32_e32 v159, v159
	v_pk_mul_f32 v[30:31], v[30:31], v[152:153]
	v_pk_mul_f32 v[32:33], v[32:33], v[154:155]
	v_pk_mul_f32 v[22:23], v[22:23], v[156:157]
	v_pk_mul_f32 v[24:25], v[24:25], v[158:159]
	v_add_u32_e32 v166, 0xa0, v146
	v_pk_mul_f32 v[26:27], v[30:31], v[26:27]
	v_pk_mul_f32 v[28:29], v[32:33], v[28:29]
	v_pk_mul_f32 v[18:19], v[22:23], v[18:19]
	v_pk_mul_f32 v[20:21], v[24:25], v[20:21]
	v_mad_i64_i32 v[164:165], s[0:1], v166, s13, v[140:141]
	v_cvt_pk_bf16_f32 v160, v26, v27
	v_cvt_pk_bf16_f32 v161, v28, v29
	v_cvt_pk_bf16_f32 v162, v18, v19
	v_cvt_pk_bf16_f32 v163, v20, v21
	v_lshl_add_u64 v[164:165], v[164:165], 0, v[184:185]
	global_store_dwordx4 v[164:165], v[160:163], off
	v_pk_mul_f32 v[168:169], v[14:15], s[100:101] op_sel_hi:[1,0]
	v_pk_mul_f32 v[170:171], v[16:17], s[100:101] op_sel_hi:[1,0]
	v_pk_mul_f32 v[172:173], v[6:7], s[100:101] op_sel_hi:[1,0]
	v_pk_mul_f32 v[174:175], v[8:9], s[100:101] op_sel_hi:[1,0]
	v_exp_f32_e32 v168, v168
	v_exp_f32_e32 v169, v169
	v_exp_f32_e32 v170, v170
	v_exp_f32_e32 v171, v171
	v_exp_f32_e32 v172, v172
	v_exp_f32_e32 v173, v173
	v_exp_f32_e32 v174, v174
	v_exp_f32_e32 v175, v175
	v_pk_add_f32 v[168:169], v[168:169], 1.0 op_sel_hi:[1,0]
	v_pk_add_f32 v[170:171], v[170:171], 1.0 op_sel_hi:[1,0]
	v_pk_add_f32 v[172:173], v[172:173], 1.0 op_sel_hi:[1,0]
	v_pk_add_f32 v[174:175], v[174:175], 1.0 op_sel_hi:[1,0]
	v_rcp_f32_e32 v168, v168
	v_rcp_f32_e32 v169, v169
	v_rcp_f32_e32 v170, v170
	v_rcp_f32_e32 v171, v171
	v_rcp_f32_e32 v172, v172
	v_rcp_f32_e32 v173, v173
	v_rcp_f32_e32 v174, v174
	v_rcp_f32_e32 v175, v175
	v_pk_mul_f32 v[14:15], v[14:15], v[168:169]
	v_pk_mul_f32 v[16:17], v[16:17], v[170:171]
	v_pk_mul_f32 v[6:7], v[6:7], v[172:173]
	v_pk_mul_f32 v[8:9], v[8:9], v[174:175]
	v_add_u32_e32 v182, 0xb0, v146
	v_pk_mul_f32 v[10:11], v[14:15], v[10:11]
	v_pk_mul_f32 v[12:13], v[16:17], v[12:13]
	v_pk_mul_f32 v[2:3], v[6:7], v[2:3]
	v_pk_mul_f32 v[4:5], v[8:9], v[4:5]
	v_mad_i64_i32 v[180:181], s[0:1], v182, s13, v[140:141]
	v_cvt_pk_bf16_f32 v176, v10, v11
	v_cvt_pk_bf16_f32 v177, v12, v13
	v_cvt_pk_bf16_f32 v178, v2, v3
	v_cvt_pk_bf16_f32 v179, v4, v5
	v_lshl_add_u64 v[180:181], v[180:181], 0, v[184:185]
	global_store_dwordx4 v[180:181], v[176:179], off
	s_cbranch_vccnz .LBB0_1590
	s_andn2_b64 vcc, exec, s[10:11]
	s_cbranch_vccnz .LBB0_1589
	s_barrier
	s_branch .LBB0_1589
